# in-proj: LDS-DMA via scalar base + 32-bit lane offsets, m0 stepped by s_add (no 64-bit VALU address math per piece)
# speedup vs baseline: 1.0624x; 1.0109x over previous
; DEVI char* wsp(const Params& P, size_t off) { asm volatile("" : "+s"(off)); return P.ws + off; }
; DEVI int ltid() { int t = threadIdx.x; asm volatile("" : "+v"(t)); return t; }
; #define ZERO_ACC(a) _Pragma("unroll") for (int m_ = 0; m_ < 4; ++m_) _Pragma("unroll") for (int n_ = 0; n_ < 4; ++n_) a[m_][n_] = f32x4{0.f, 0.f, 0.f, 0.f}
; DEVI void stage_tile(const bfu* __restrict__ g, int ld, int k0, char* lds, int tid) {
; #pragma unroll
;   for (int i = 0; i < 4; ++i) {
;     int b = tid * 16 + i * 4096;
;     int r = b >> 7, cp = (b >> 4) & 7, gc = cp ^ (r & 7);
;     __builtin_amdgcn_global_load_lds((const unsigned*)(g + (long)r * ld + k0 + gc * 8),
;                                      (unsigned*)(lds + b), 16, 0, 0);
;   }
; }
; DEVI void phase_inproj(const Params& P, int l, int pass, char* smem) {
;   const int tid = ltid();
;   const int ntok = pass ? 8192 : 8448, base = pass ? 8448 : 0;
;   const int nM = ntok / 128, nN = 96;
;   const bfu* xb = (const bfu*)wsp(P, O_XB) + (long)base * 1024;
;   const bfu* wT = (const bfu*)wsp(P, O_WIN);
;   bfu* z = (bfu*)wsp(P, O_Z);
;   const float* bin = P.in[7] + l * NCOL;
;   for (int id = blockIdx.x; id < nM * nN; id += gridDim.x) {
;     int pm, pn; tile_rc(id, nM, nN, pm, pn);
;     f32x4 acc[4][4]; ZERO_ACC(acc);
;     gemm_core(acc, xb + (long)pm * 128 * 1024, 1024, wT + (long)pn * 128 * 1024, 1024, 1024, smem, tid);
.LBB0_277:
	s_andn2_b64 vcc, exec, s[40:41]
	s_cbranch_vccnz .LBB0_298
	s_andn2_b64 vcc, exec, s[6:7]
	s_cbranch_vccnz .LBB0_297
	s_mov_b32 s0, s51
	s_cmp_eq_u32 s0, 0
	s_cselect_b64 s[42:43], -1, 0
	s_and_b64 s[0:1], s[42:43], exec
	s_cselect_b32 s49, 0x42, 64
	s_mul_i32 s46, s49, 0x60
	v_readlane_b32 s50, v252, 32
	v_mov_b32_e32 v0, v93
	s_mov_b64 s[40:41], 0x6502000
	s_mov_b64 s[0:1], 0
	s_mov_b64 s[44:45], 0x8582000
	s_cmp_ge_i32 s50, s46
	s_cbranch_scc1 .LBB0_297
	v_lshlrev_b32_e32 v91, 4, v0
	v_add_u32_e32 v172, 0x2000, v91
	v_ashrrev_i32_e32 v14, 7, v172
	v_lshrrev_b32_e32 v1, 4, v0
	v_xor_b32_e32 v13, v14, v0
	v_add_u32_e32 v173, 0x3000, v91
	v_and_b32_e32 v25, 7, v0
	v_lshlrev_b32_e32 v13, 3, v13
	v_ashrrev_i32_e32 v20, 7, v173
	v_bitop3_b32 v1, v1, v25, 3 bitop3:0x6c
	v_bfe_u32 v7, v0, 4, 2
	v_and_b32_e32 v18, 56, v13
	v_xor_b32_e32 v13, v20, v0
	v_lshlrev_b32_e32 v174, 4, v1
	v_lshlrev_b32_e32 v1, 7, v0
	v_readlane_b32 s4, v254, 44
	v_lshlrev_b32_e32 v13, 3, v13
	v_and_b32_e32 v176, 0x2780, v1
	v_bitop3_b32 v1, v7, v25, 4 bitop3:0x36
	v_and_b32_e32 v24, 56, v13
	v_and_b32_e32 v13, 15, v0
	v_lshrrev_b32_e32 v19, 1, v0
	s_mov_b32 s4, 0x1ffffc0
	v_lshlrev_b32_e32 v177, 4, v1
	v_lshrrev_b32_e32 v1, 2, v0
	s_and_b64 s[42:43], s[42:43], exec
	v_and_or_b32 v13, v19, s4, v13
	v_and_b32_e32 v1, 12, v1
	s_mov_b32 s4, 0xfffffc0
	s_mul_i32 s42, s2, 0x3000
	v_and_or_b32 v1, v19, s4, v1
	s_movk_i32 s4, 0x110
	s_cselect_b32 s24, 0, 0x1080000
	s_ashr_i32 s43, s42, 31
	v_and_b32_e32 v106, 0x4f, v0
	v_mul_lo_u32 v1, v1, s4
	s_lshl_b64 s[42:43], s[42:43], 2
	v_readlane_b32 s14, v254, 54
	v_lshl_add_u32 v178, v106, 1, v1
	v_lshlrev_b32_e32 v1, 3, v0
	v_readlane_b32 s15, v254, 55
	s_add_u32 s47, s14, s42
	v_and_b32_e32 v26, 0x78, v1
	v_ashrrev_i32_e32 v1, 4, v0
	s_addc_u32 s48, s15, s43
	v_lshlrev_b32_e32 v175, 7, v13
	v_mul_lo_u32 v13, v1, s4
	v_mad_i64_i32 v[108:109], s[42:43], v1, s22, 0
	v_add_u32_e32 v1, 0x100, v0
	v_ashrrev_i32_e32 v1, 4, v1
	v_mul_lo_u32 v19, v1, s4
	v_mad_i64_i32 v[110:111], s[42:43], v1, s22, 0
	v_add_u32_e32 v1, 0x200, v0
	v_ashrrev_i32_e32 v1, 4, v1
	v_mul_lo_u32 v25, v1, s4
	v_mad_i64_i32 v[112:113], s[42:43], v1, s22, 0
	v_add_u32_e32 v1, 0x300, v0
	v_ashrrev_i32_e32 v1, 4, v1
	v_mul_lo_u32 v27, v1, s4
	v_mad_i64_i32 v[114:115], s[42:43], v1, s22, 0
	v_add_u32_e32 v1, 0x400, v0
	v_ashrrev_i32_e32 v1, 4, v1
	v_mul_lo_u32 v36, v1, s4
	v_mad_i64_i32 v[116:117], s[42:43], v1, s22, 0
	v_add_u32_e32 v1, 0x500, v0
	v_ashrrev_i32_e32 v1, 4, v1
	v_mul_lo_u32 v37, v1, s4
	v_mad_i64_i32 v[118:119], s[42:43], v1, s22, 0
	v_add_u32_e32 v1, 0x600, v0
	v_lshl_add_u64 v[2:3], v[64:65], 0, s[40:41]
	v_ashrrev_i32_e32 v1, 4, v1
	v_lshl_add_u64 v[100:101], v[2:3], 0, s[24:25]
	v_ashrrev_i32_e32 v2, 3, v0
	v_mul_lo_u32 v38, v1, s4
	v_mad_i64_i32 v[120:121], s[42:43], v1, s22, 0
	v_add_u32_e32 v1, 0x700, v0
	v_ashrrev_i32_e32 v3, 31, v2
	v_ashrrev_i32_e32 v1, 4, v1
	v_mul_lo_u32 v39, v1, s4
	v_mad_i64_i32 v[122:123], s[42:43], v1, s22, 0
	v_lshlrev_b64 v[28:29], 11, v[2:3]
	v_bitop3_b32 v1, v2, 7, v0 bitop3:0x48
	v_add_u32_e32 v107, 0x1000, v91
	v_lshl_add_u64 v[30:31], s[40:41], 0, v[28:29]
	v_lshlrev_b32_e32 v88, 4, v1
	v_xor_b32_e32 v6, v2, v0
	v_lshlrev_b64 v[4:5], 10, v[2:3]
	v_ashrrev_i32_e32 v8, 7, v107
	v_lshl_add_u64 v[2:3], v[30:31], 0, v[88:89]
	v_ashrrev_i32_e32 v9, 31, v8
	v_lshl_add_u64 v[2:3], v[2:3], 0, s[24:25]
	v_lshl_add_u64 v[124:125], v[86:87], 0, v[2:3]
	v_lshlrev_b64 v[2:3], 11, v[8:9]
	v_bitop3_b32 v1, v8, 7, v0 bitop3:0x48
	v_xor_b32_e32 v12, v8, v0
	v_lshlrev_b64 v[10:11], 10, v[8:9]
	v_lshl_add_u64 v[30:31], s[40:41], 0, v[2:3]
	v_lshlrev_b32_e32 v8, 4, v1
	v_mov_b32_e32 v9, v89
	v_lshl_add_u64 v[30:31], v[30:31], 0, v[8:9]
	v_ashrrev_i32_e32 v15, 31, v14
	v_lshl_add_u64 v[30:31], v[30:31], 0, s[24:25]
	v_lshl_add_u64 v[126:127], v[86:87], 0, v[30:31]
	v_lshlrev_b64 v[30:31], 11, v[14:15]
	v_bitop3_b32 v1, v14, 7, v0 bitop3:0x48
	v_lshlrev_b64 v[16:17], 10, v[14:15]
	v_lshl_add_u64 v[32:33], s[40:41], 0, v[30:31]
	v_lshlrev_b32_e32 v14, 4, v1
	v_mov_b32_e32 v15, v89
	v_lshl_add_u64 v[32:33], v[32:33], 0, v[14:15]
	v_ashrrev_i32_e32 v21, 31, v20
	v_lshl_add_u64 v[32:33], v[32:33], 0, s[24:25]
	v_lshl_add_u64 v[128:129], v[86:87], 0, v[32:33]
	v_lshlrev_b64 v[32:33], 11, v[20:21]
	v_bitop3_b32 v0, v20, 7, v0 bitop3:0x48
	v_lshl_add_u64 v[2:3], s[0:1], 0, v[2:3]
	s_add_i32 s49, s49, 0xffc0
	v_lshl_add_u64 v[34:35], s[40:41], 0, v[32:33]
	v_lshlrev_b32_e32 v0, 4, v0
	v_mov_b32_e32 v1, v89
	v_lshl_add_u64 v[2:3], v[2:3], 0, v[8:9]
	v_lshlrev_b64 v[22:23], 10, v[20:21]
	v_cvt_f32_ubyte0_e32 v179, s49
	v_lshl_add_u64 v[20:21], v[34:35], 0, v[0:1]
	v_lshl_add_u64 v[134:135], v[86:87], 0, v[2:3]
	v_lshl_add_u64 v[2:3], s[0:1], 0, v[30:31]
	v_rcp_iflag_f32_e32 v180, v179
	v_lshl_add_u64 v[20:21], v[20:21], 0, s[24:25]
	v_lshl_add_u64 v[2:3], v[2:3], 0, v[14:15]
	v_lshlrev_b32_e32 v6, 3, v6
	v_lshlrev_b32_e32 v12, 3, v12
	v_lshl_add_u64 v[130:131], v[86:87], 0, v[20:21]
	v_lshl_add_u64 v[20:21], s[0:1], 0, v[28:29]
	v_lshl_add_u64 v[136:137], v[86:87], 0, v[2:3]
	v_lshl_add_u64 v[2:3], s[0:1], 0, v[32:33]
	v_and_b32_e32 v6, 56, v6
	v_and_b32_e32 v12, 56, v12
	v_lshlrev_b32_e32 v7, 1, v26
	v_lshl_add_u64 v[20:21], v[20:21], 0, v[88:89]
	v_lshl_add_u64 v[0:1], v[2:3], 0, v[0:1]
	v_lshl_add_u64 v[102:103], v[64:65], 0, s[0:1]
	v_lshl_add_u64 v[104:105], v[64:65], 0, s[44:45]
	s_movk_i32 s37, 0x110
	v_lshl_add_u64 v[132:133], v[86:87], 0, v[20:21]
	v_lshl_add_u64 v[138:139], v[86:87], 0, v[0:1]
	v_lshlrev_b64 v[140:141], 1, v[4:5]
	v_lshlrev_b32_e32 v142, 1, v6
	v_lshlrev_b64 v[144:145], 1, v[10:11]
	v_lshlrev_b32_e32 v146, 1, v12
	v_lshlrev_b64 v[148:149], 1, v[16:17]
	v_lshlrev_b32_e32 v150, 1, v18
	v_lshlrev_b64 v[152:153], 1, v[22:23]
	v_lshlrev_b32_e32 v154, 1, v24
	v_lshlrev_b32_e32 v88, 1, v26
	v_add_u32_e32 v181, v7, v13
	v_add_u32_e32 v182, v7, v19
	v_add_u32_e32 v183, v7, v25
	v_add_u32_e32 v196, v7, v27
	v_add_u32_e32 v197, v7, v36
	v_add_u32_e32 v198, v7, v37
	v_add_u32_e32 v199, v7, v38
	v_add_u32_e32 v200, v7, v39
	s_mov_b32 s24, s50
	v_readlane_b32 s5, v254, 45
	v_readlane_b32 s6, v254, 46
	v_readlane_b32 s7, v254, 47
	v_readlane_b32 s8, v254, 48
	v_readlane_b32 s9, v254, 49
	v_readlane_b32 s10, v254, 50
	v_readlane_b32 s11, v254, 51
	v_readlane_b32 s12, v254, 52
	v_readlane_b32 s13, v254, 53
	v_readlane_b32 s16, v254, 56
	v_readlane_b32 s17, v254, 57
	v_readlane_b32 s18, v254, 58
	v_readlane_b32 s19, v254, 59
	v_add_u32_e32 v201, v140, v142
	v_add_u32_e32 v250, v144, v146
	v_add_u32_e32 v251, v148, v150
	v_add_u32_e32 v255, v152, v154
	v_readfirstlane_b32 s60, v100
	v_readfirstlane_b32 s61, v101
	v_readfirstlane_b32 s62, v102
	v_readfirstlane_b32 s63, v103
	s_branch .LBB0_282

; DEVI void stage_tile(const bfu* __restrict__ g, int ld, int k0, char* lds, int tid) {
; #pragma unroll
;   for (int i = 0; i < 4; ++i) {
;     int b = tid * 16 + i * 4096;
;     int r = b >> 7, cp = (b >> 4) & 7, gc = cp ^ (r & 7);
;     __builtin_amdgcn_global_load_lds((const unsigned*)(g + (long)r * ld + k0 + gc * 8),
;                                      (unsigned*)(lds + b), 16, 0, 0);
;   }
; }
; template <int GATE>
; DEVI void gemm_core_t(f32x4 (&acc)[4][4], const bfu* __restrict__ A, int lda,
;                     const bfu* __restrict__ B, int ldb, int K, char* smem, int tid, const bfu* __restrict__ B2 = nullptr) {
;     ...
;   const int nt = K >> 6;
;   __syncthreads();
;   stage_tile(A, lda, 0, smem, tid);
;   if (GATE) stage_tile_gate(B, B2, 0, smem + 16384, tid); else stage_tile(B, ldb, 0, smem + 16384, tid);
;   for (int t = 0; t < nt; ++t) {
;     asm volatile("s_waitcnt vmcnt(0)" ::: "memory");
;     __syncthreads();
;     char* cur = smem + (t & 1) * 32768;
;     if (t + 1 < nt) {
;       char* nx = smem + ((t + 1) & 1) * 32768;
;       stage_tile(A, lda, (t + 1) * 64, nx, tid);
;       if (GATE) stage_tile_gate(B, B2, (t + 1) * 64, nx + 16384, tid); else stage_tile(B, ldb, (t + 1) * 64, nx + 16384, tid);
;     }
.LBB0_286:
	s_and_b32 s1, s50, 7
	s_or_b32 s40, s42, s1
	s_ashr_i32 s1, s0, 31
	s_lshl_b64 s[44:45], s[0:1], 18
	s_ashr_i32 s41, s40, 31
	s_lshl_b64 s[52:53], s[40:41], 18
	s_add_u32 s56, s60, s44
	s_addc_u32 s57, s61, s45
	s_add_u32 s58, s62, s52
	s_addc_u32 s59, s63, s53
	v_readfirstlane_b32 s1, v91
	s_nop 0
	s_mov_b32 m0, s1
	s_barrier
	global_load_lds_dwordx4 v201, s[56:57]
	s_add_u32 m0, m0, 0x1000
	s_nop 0
	global_load_lds_dwordx4 v250, s[56:57]
	s_add_u32 m0, m0, 0x1000
	s_nop 0
	global_load_lds_dwordx4 v251, s[56:57]
	s_add_u32 m0, m0, 0x1000
	s_nop 0
	global_load_lds_dwordx4 v255, s[56:57]
	s_add_u32 m0, m0, 0x1000
	s_nop 0
	global_load_lds_dwordx4 v201, s[58:59]
	s_add_u32 m0, m0, 0x1000
	s_nop 0
	global_load_lds_dwordx4 v250, s[58:59]
	s_add_u32 m0, m0, 0x1000
	s_nop 0
	global_load_lds_dwordx4 v251, s[58:59]
	s_add_u32 m0, m0, 0x1000
	s_nop 0
	global_load_lds_dwordx4 v255, s[58:59]
	s_add_u32 m0, m0, 0x1000
	s_nop 0
	s_add_u32 s56, s56, 0x80
	s_addc_u32 s57, s57, 0
	s_add_u32 s58, s58, 0x80
	s_addc_u32 s59, s59, 0
	v_mov_b32_e32 v0, 0
	s_mov_b64 s[42:43], 0
	s_mov_b32 s1, 0x8000
	v_mov_b32_e32 v1, v0
	v_mov_b32_e32 v2, v0
	v_mov_b32_e32 v3, v0
	v_mov_b32_e32 v4, v0
	v_mov_b32_e32 v5, v0
	v_mov_b32_e32 v6, v0
	v_mov_b32_e32 v7, v0
	v_mov_b32_e32 v8, v0
	v_mov_b32_e32 v9, v0
	v_mov_b32_e32 v10, v0
	v_mov_b32_e32 v11, v0
	v_mov_b32_e32 v12, v0
	v_mov_b32_e32 v13, v0
	v_mov_b32_e32 v14, v0
	v_mov_b32_e32 v15, v0
	v_mov_b32_e32 v16, v0
	v_mov_b32_e32 v17, v0
	v_mov_b32_e32 v18, v0
	v_mov_b32_e32 v19, v0
	v_mov_b32_e32 v20, v0
	v_mov_b32_e32 v21, v0
	v_mov_b32_e32 v22, v0
	v_mov_b32_e32 v23, v0
	v_mov_b32_e32 v24, v0
	v_mov_b32_e32 v25, v0
	v_mov_b32_e32 v26, v0
	v_mov_b32_e32 v27, v0
	v_mov_b32_e32 v28, v0
	v_mov_b32_e32 v29, v0
	v_mov_b32_e32 v30, v0
	v_mov_b32_e32 v31, v0
	v_mov_b32_e32 v32, v0
	v_mov_b32_e32 v33, v0
	v_mov_b32_e32 v34, v0
	v_mov_b32_e32 v35, v0
	v_mov_b32_e32 v36, v0
	v_mov_b32_e32 v37, v0
	v_mov_b32_e32 v38, v0
	v_mov_b32_e32 v39, v0
	v_mov_b32_e32 v40, v0
	v_mov_b32_e32 v41, v0
	v_mov_b32_e32 v42, v0
	v_mov_b32_e32 v43, v0
	v_mov_b32_e32 v44, v0
	v_mov_b32_e32 v45, v0
	v_mov_b32_e32 v46, v0
	v_mov_b32_e32 v47, v0
	v_mov_b32_e32 v48, v0
	v_mov_b32_e32 v49, v0
	v_mov_b32_e32 v50, v0
	v_mov_b32_e32 v51, v0
	v_mov_b32_e32 v52, v0
	v_mov_b32_e32 v53, v0
	v_mov_b32_e32 v54, v0
	v_mov_b32_e32 v55, v0
	v_mov_b32_e32 v56, v0
	v_mov_b32_e32 v57, v0
	v_mov_b32_e32 v58, v0
	v_mov_b32_e32 v59, v0
	v_mov_b32_e32 v60, v0
	v_mov_b32_e32 v61, v0
	v_mov_b32_e32 v62, v0
	v_mov_b32_e32 v63, v0
.LBB0_287:
	s_add_i32 s41, s1, 0xffff8000
	s_and_b32 s44, s41, 0x8000
	s_and_b32 s41, s1, 0x8000
	v_add_u32_e32 v143, s41, v91
	v_or_b32_e32 v147, s44, v174
	v_readfirstlane_b32 s45, v143
	v_add_u32_e32 v143, v147, v175
	v_add_u32_e32 v147, v147, v176
	s_waitcnt vmcnt(0)
	s_waitcnt vmcnt(0) lgkmcnt(0)
	s_barrier
	ds_read_b128 v[202:205], v143
	ds_read_b128 v[218:221], v147 offset:16384
	ds_read_b128 v[222:225], v147 offset:18432
	ds_read_b128 v[226:229], v147 offset:20480
	ds_read_b128 v[230:233], v147 offset:22528
	ds_read_b128 v[206:209], v143 offset:2048
	ds_read_b128 v[210:213], v143 offset:4096
	ds_read_b128 v[214:217], v143 offset:6144
	s_mov_b32 m0, s45
	s_nop 0
	global_load_lds_dwordx4 v201, s[56:57]
	s_add_u32 m0, m0, 0x1000
	v_or_b32_e32 v147, s44, v177
	v_add_u32_e32 v143, v147, v175
	v_add_u32_e32 v147, v147, v176
	ds_read_b128 v[234:237], v147 offset:16384
	ds_read_b128 v[238:241], v147 offset:18432
	ds_read_b128 v[242:245], v147 offset:20480
	ds_read_b128 v[246:249], v147 offset:22528
	global_load_lds_dwordx4 v250, s[56:57]
	s_add_u32 m0, m0, 0x1000
	s_waitcnt lgkmcnt(7)
	v_mfma_f32_16x16x32_bf16 v[60:63], v[202:205], v[218:221], v[60:63]
	v_mfma_f32_16x16x32_bf16 v[56:59], v[202:205], v[222:225], v[56:59]
	v_mfma_f32_16x16x32_bf16 v[52:55], v[202:205], v[226:229], v[52:55]
	v_mfma_f32_16x16x32_bf16 v[48:51], v[202:205], v[230:233], v[48:51]
	ds_read_b128 v[202:205], v143
	global_load_lds_dwordx4 v251, s[56:57]
	s_add_u32 m0, m0, 0x1000
	s_waitcnt lgkmcnt(7)
	v_mfma_f32_16x16x32_bf16 v[44:47], v[206:209], v[218:221], v[44:47]
	v_mfma_f32_16x16x32_bf16 v[40:43], v[206:209], v[222:225], v[40:43]
	v_mfma_f32_16x16x32_bf16 v[36:39], v[206:209], v[226:229], v[36:39]
	v_mfma_f32_16x16x32_bf16 v[32:35], v[206:209], v[230:233], v[32:35]
	ds_read_b128 v[206:209], v143 offset:2048
	global_load_lds_dwordx4 v255, s[56:57]
	s_add_u32 m0, m0, 0x1000
	s_waitcnt lgkmcnt(7)
	v_mfma_f32_16x16x32_bf16 v[28:31], v[210:213], v[218:221], v[28:31]
	v_mfma_f32_16x16x32_bf16 v[24:27], v[210:213], v[222:225], v[24:27]
	v_mfma_f32_16x16x32_bf16 v[20:23], v[210:213], v[226:229], v[20:23]
	v_mfma_f32_16x16x32_bf16 v[16:19], v[210:213], v[230:233], v[16:19]
	ds_read_b128 v[210:213], v143 offset:4096
	global_load_lds_dwordx4 v201, s[58:59]
	s_add_u32 m0, m0, 0x1000
	s_waitcnt lgkmcnt(7)
	v_mfma_f32_16x16x32_bf16 v[12:15], v[214:217], v[218:221], v[12:15]
	v_mfma_f32_16x16x32_bf16 v[8:11], v[214:217], v[222:225], v[8:11]
	v_mfma_f32_16x16x32_bf16 v[4:7], v[214:217], v[226:229], v[4:7]
	v_mfma_f32_16x16x32_bf16 v[0:3], v[214:217], v[230:233], v[0:3]
	ds_read_b128 v[214:217], v143 offset:6144
	global_load_lds_dwordx4 v250, s[58:59]
	s_add_u32 m0, m0, 0x1000
	s_waitcnt lgkmcnt(3)
	v_mfma_f32_16x16x32_bf16 v[60:63], v[202:205], v[234:237], v[60:63]
	v_mfma_f32_16x16x32_bf16 v[56:59], v[202:205], v[238:241], v[56:59]
	v_mfma_f32_16x16x32_bf16 v[52:55], v[202:205], v[242:245], v[52:55]
	v_mfma_f32_16x16x32_bf16 v[48:51], v[202:205], v[246:249], v[48:51]
	global_load_lds_dwordx4 v251, s[58:59]
	s_add_u32 m0, m0, 0x1000
	s_waitcnt lgkmcnt(2)
	v_mfma_f32_16x16x32_bf16 v[44:47], v[206:209], v[234:237], v[44:47]
	v_mfma_f32_16x16x32_bf16 v[40:43], v[206:209], v[238:241], v[40:43]
	v_mfma_f32_16x16x32_bf16 v[36:39], v[206:209], v[242:245], v[36:39]
	v_mfma_f32_16x16x32_bf16 v[32:35], v[206:209], v[246:249], v[32:35]
	global_load_lds_dwordx4 v255, s[58:59]
	s_waitcnt lgkmcnt(1)
	v_mfma_f32_16x16x32_bf16 v[28:31], v[210:213], v[234:237], v[28:31]
	v_mfma_f32_16x16x32_bf16 v[24:27], v[210:213], v[238:241], v[24:27]
	v_mfma_f32_16x16x32_bf16 v[20:23], v[210:213], v[242:245], v[20:23]
	v_mfma_f32_16x16x32_bf16 v[16:19], v[210:213], v[246:249], v[16:19]
	s_waitcnt lgkmcnt(0)
	v_mfma_f32_16x16x32_bf16 v[12:15], v[214:217], v[234:237], v[12:15]
	v_mfma_f32_16x16x32_bf16 v[8:11], v[214:217], v[238:241], v[8:11]
	v_mfma_f32_16x16x32_bf16 v[4:7], v[214:217], v[242:245], v[4:7]
	v_mfma_f32_16x16x32_bf16 v[0:3], v[214:217], v[246:249], v[0:3]
	s_add_u32 s56, s56, 0x80
	s_addc_u32 s57, s57, 0
	s_add_u32 s58, s58, 0x80
	s_addc_u32 s59, s59, 0
	s_add_u32 s42, s42, 0x80
	s_addc_u32 s43, s43, 0
	s_add_i32 s1, s1, 0x8000
	s_cmpk_lg_i32 s42, 0x780
	s_cbranch_scc1 .LBB0_287
; template <int GATE>
; DEVI void gemm_core_t(f32x4 (&acc)[4][4], const bfu* __restrict__ A, int lda,
;                     const bfu* __restrict__ B, int ldb, int K, char* smem, int tid, const bfu* __restrict__ B2 = nullptr) {
;     ...
; #pragma unroll
;     for (int kk = 0; kk < 2; ++kk) {
;       bf16x8 af[4], bfr[4];
; #pragma unroll
;       for (int m = 0; m < 4; ++m) af[m] = ldfrag(cur, wr * 64 + m * 16 + fr, kk * 4 + fq);
; #pragma unroll
;       for (int n = 0; n < 4; ++n) bfr[n] = ldfrag(cur + 16384, wc * 64 + n * 16 + fr, kk * 4 + fq);
; #pragma unroll
;       for (int m = 0; m < 4; ++m)
; #pragma unroll
;         for (int n = 0; n < 4; ++n)
;           acc[m][n] = __builtin_amdgcn_mfma_f32_16x16x32_bf16(af[m], bfr[n], acc[m][n], 0, 0, 0);
;     }
; DEVI void epi_store_bf16(const f32x4 (&acc)[4][4], const float* colbias, bfu* dst, long ld, char* smem, int tid) {
;   const int wid = tid >> 6, lane = tid & 63, wr = wid >> 1, wc = wid & 1, fr = lane & 15, fq = lane >> 4;
;   bfu* T = reinterpret_cast<bfu*>(smem);
;   __syncthreads();
; #pragma unroll
;   for (int n = 0; n < 4; ++n) {
;     const int col = wc * 64 + n * 16 + fr;
;     const float bias = colbias ? colbias[col] : 0.f;
	v_add_u32_e32 v143, s41, v174
	v_add_u32_e32 v147, v143, v175
	s_waitcnt vmcnt(0)
	s_waitcnt vmcnt(0)
	s_barrier
	ds_read_b128 v[156:159], v147
	v_add_u32_e32 v143, v143, v176
	ds_read_b128 v[168:171], v143 offset:20480
	ds_read_b128 v[160:163], v143 offset:16384
	ds_read_b128 v[164:167], v143 offset:18432
	s_waitcnt lgkmcnt(2)
	v_mfma_f32_16x16x32_bf16 v[202:205], v[156:159], v[168:171], v[52:55]
	s_nop 2
	ds_read_b128 v[52:55], v143 offset:22528
	s_lshl_b32 s42, s40, 7
	s_ashr_i32 s43, s42, 31
	s_waitcnt lgkmcnt(2)
	v_mfma_f32_16x16x32_bf16 v[60:63], v[156:159], v[160:163], v[60:63]
	v_readlane_b32 s4, v254, 60
	v_readlane_b32 s5, v254, 61
	v_mov_b32_e32 v151, 0
	s_waitcnt lgkmcnt(1)
	v_mfma_f32_16x16x32_bf16 v[56:59], v[156:159], v[164:167], v[56:59]
	s_waitcnt lgkmcnt(0)
	v_mfma_f32_16x16x32_bf16 v[48:51], v[156:159], v[52:55], v[48:51]
	ds_read_b128 v[156:159], v147 offset:2048
	s_waitcnt lgkmcnt(0)
	v_mfma_f32_16x16x32_bf16 v[206:209], v[156:159], v[168:171], v[36:39]
	s_nop 2
	ds_read_b128 v[36:39], v147 offset:4096
	s_waitcnt lgkmcnt(0)
	v_mfma_f32_16x16x32_bf16 v[214:217], v[36:39], v[52:55], v[16:19]
	s_nop 2
	ds_read_b128 v[16:19], v147 offset:6144
	v_mov_b32_e32 v147, 0
	v_mfma_f32_16x16x32_bf16 v[44:47], v[156:159], v[160:163], v[44:47]
	v_mfma_f32_16x16x32_bf16 v[28:31], v[36:39], v[160:163], v[28:31]
	s_waitcnt lgkmcnt(0)
	v_mfma_f32_16x16x32_bf16 v[12:15], v[16:19], v[160:163], v[12:15]
	v_mfma_f32_16x16x32_bf16 v[160:163], v[16:19], v[164:167], v[8:11]
	s_nop 2
	v_add_u32_e32 v8, s41, v177
	v_add_u32_e32 v143, v8, v175
	v_mfma_f32_16x16x32_bf16 v[40:43], v[156:159], v[164:167], v[40:43]
	s_lshl_b64 s[40:41], s[42:43], 2
	s_add_u32 s44, s47, s40
	s_addc_u32 s45, s48, s41
	v_lshlrev_b32_e32 v236, 2, v106
	global_load_dword v151, v236, s[44:45]
	global_load_dword v147, v236, s[44:45] offset:64
	global_load_dword v234, v236, s[44:45] offset:128
	global_load_dword v235, v236, s[44:45] offset:192
	v_mfma_f32_16x16x32_bf16 v[32:35], v[156:159], v[52:55], v[32:35]
	s_andn2_b64 vcc, exec, s[4:5]
	v_mfma_f32_16x16x32_bf16 v[156:159], v[36:39], v[164:167], v[24:27]
	v_mfma_f32_16x16x32_bf16 v[164:167], v[16:19], v[168:171], v[4:7]
	s_nop 2
	ds_read_b128 v[4:7], v143
	v_mfma_f32_16x16x32_bf16 v[210:213], v[36:39], v[168:171], v[20:23]
	v_mfma_f32_16x16x32_bf16 v[168:171], v[16:19], v[52:55], v[0:3]
	s_nop 2
	v_add_u32_e32 v0, v8, v176
	ds_read_b128 v[226:229], v0 offset:20480
	ds_read_b128 v[218:221], v0 offset:16384
	ds_read_b128 v[222:225], v0 offset:18432
	s_waitcnt lgkmcnt(2)
	v_mfma_f32_16x16x32_bf16 v[20:23], v[4:7], v[226:229], v[202:205]
	ds_read_b128 v[8:11], v143 offset:4096
	s_nop 1
	ds_read_b128 v[202:205], v0 offset:22528
	s_waitcnt lgkmcnt(3)
	v_mfma_f32_16x16x32_bf16 v[52:55], v[4:7], v[218:221], v[60:63]
	s_waitcnt lgkmcnt(2)
	v_mfma_f32_16x16x32_bf16 v[36:39], v[4:7], v[222:225], v[56:59]
	s_waitcnt lgkmcnt(0)
	v_mfma_f32_16x16x32_bf16 v[0:3], v[4:7], v[202:205], v[48:51]
	ds_read_b128 v[4:7], v143 offset:2048
	s_waitcnt lgkmcnt(0)
	v_mfma_f32_16x16x32_bf16 v[60:63], v[4:7], v[218:221], v[44:47]
	v_mfma_f32_16x16x32_bf16 v[40:43], v[4:7], v[222:225], v[40:43]
	v_mfma_f32_16x16x32_bf16 v[24:27], v[4:7], v[226:229], v[206:209]
	v_mfma_f32_16x16x32_bf16 v[4:7], v[4:7], v[202:205], v[32:35]
	v_mfma_f32_16x16x32_bf16 v[32:35], v[8:11], v[222:225], v[156:159]
	s_nop 2
	ds_read_b128 v[156:159], v143 offset:6144
	s_waitcnt lgkmcnt(0)
	v_mfma_f32_16x16x32_bf16 v[56:59], v[156:159], v[218:221], v[12:15]
	s_nop 2
	v_cndmask_b32_e64 v12, 0, 1, s[4:5]
	v_cmp_ne_u32_e64 s[40:41], 1, v12
	v_lshlrev_b32_e32 v143, 2, v106
	v_mfma_f32_16x16x32_bf16 v[48:51], v[8:11], v[218:221], v[28:31]
	s_barrier
	v_mfma_f32_16x16x32_bf16 v[16:19], v[8:11], v[226:229], v[210:213]
	v_mfma_f32_16x16x32_bf16 v[8:11], v[8:11], v[202:205], v[214:217]
	v_mfma_f32_16x16x32_bf16 v[44:47], v[156:159], v[222:225], v[160:163]
	v_mfma_f32_16x16x32_bf16 v[28:31], v[156:159], v[226:229], v[164:167]
	v_mfma_f32_16x16x32_bf16 v[12:15], v[156:159], v[202:205], v[168:171]

; __global__ void __launch_bounds__(256, 2) fwd_megakernel(Params P) {
;   __shared__ __attribute__((aligned(16))) char smem[65536];
	.amdhsa_kernel _Z14fwd_megakernel6Params
		.amdhsa_group_segment_fixed_size 65536
		.amdhsa_private_segment_fixed_size 0
		.amdhsa_kernarg_size 512
		.amdhsa_user_sgpr_count 2
		.amdhsa_user_sgpr_dispatch_ptr 0
		.amdhsa_user_sgpr_queue_ptr 0
		.amdhsa_user_sgpr_kernarg_segment_ptr 1
		.amdhsa_user_sgpr_dispatch_id 0
		.amdhsa_user_sgpr_kernarg_preload_length 0
		.amdhsa_user_sgpr_kernarg_preload_offset 0
		.amdhsa_user_sgpr_private_segment_size 0
		.amdhsa_uses_dynamic_stack 0
		.amdhsa_enable_private_segment 0
		.amdhsa_system_sgpr_workgroup_id_x 1
		.amdhsa_system_sgpr_workgroup_id_y 0
		.amdhsa_system_sgpr_workgroup_id_z 0
		.amdhsa_system_sgpr_workgroup_info 0
		.amdhsa_system_vgpr_workitem_id 2
		.amdhsa_next_free_vgpr 256
		.amdhsa_next_free_sgpr 100
		.amdhsa_accum_offset 256
		.amdhsa_reserve_vcc 1
		.amdhsa_float_round_mode_32 0
		.amdhsa_float_round_mode_16_64 0
		.amdhsa_float_denorm_mode_32 3
		.amdhsa_float_denorm_mode_16_64 3
		.amdhsa_dx10_clamp 1
		.amdhsa_ieee_mode 1
		.amdhsa_fp16_overflow 0
		.amdhsa_tg_split 0
		.amdhsa_exception_fp_ieee_invalid_op 0
		.amdhsa_exception_fp_denorm_src 0
		.amdhsa_exception_fp_ieee_div_zero 0
		.amdhsa_exception_fp_ieee_overflow 0
		.amdhsa_exception_fp_ieee_underflow 0
		.amdhsa_exception_fp_ieee_inexact 0
		.amdhsa_exception_int_div_zero 0
	.end_amdhsa_kernel

; __global__ void __launch_bounds__(256, 2) fwd_megakernel(Params P) {
;   __shared__ __attribute__((aligned(16))) char smem[65536];
amdhsa.kernels:
  - .agpr_count:     0
    .args:
      - .offset:         0
        .size:           256
        .value_kind:     by_value
      - .offset:         256
        .size:           4
        .value_kind:     hidden_block_count_x
      - .offset:         260
        .size:           4
        .value_kind:     hidden_block_count_y
      - .offset:         264
        .size:           4
        .value_kind:     hidden_block_count_z
      - .offset:         268
        .size:           2
        .value_kind:     hidden_group_size_x
      - .offset:         270
        .size:           2
        .value_kind:     hidden_group_size_y
      - .offset:         272
        .size:           2
        .value_kind:     hidden_group_size_z
      - .offset:         274
        .size:           2
        .value_kind:     hidden_remainder_x
      - .offset:         276
        .size:           2
        .value_kind:     hidden_remainder_y
      - .offset:         278
        .size:           2
        .value_kind:     hidden_remainder_z
      - .offset:         296
        .size:           8
        .value_kind:     hidden_global_offset_x
      - .offset:         304
        .size:           8
        .value_kind:     hidden_global_offset_y
      - .offset:         312
        .size:           8
        .value_kind:     hidden_global_offset_z
      - .offset:         320
        .size:           2
        .value_kind:     hidden_grid_dims
      - .offset:         344
        .size:           8
        .value_kind:     hidden_multigrid_sync_arg
    .group_segment_fixed_size: 65536
    .kernarg_segment_align: 8
    .kernarg_segment_size: 512
    .language:       OpenCL C
    .language_version:
      - 2
      - 0
    .max_flat_workgroup_size: 256
    .name:           _Z14fwd_megakernel6Params
    .private_segment_fixed_size: 0
    .sgpr_count:     106
    .sgpr_spill_count: 191
    .symbol:         _Z14fwd_megakernel6Params.kd
    .uniform_work_group_size: 1
    .uses_dynamic_stack: false
    .vgpr_count:     256
    .vgpr_spill_count: 0
    .wavefront_size: 64
